# intra-chunk score tiles stored in MFMA-fragment order by their producer; the retention scan feeds them to the MFMA straight from the coalesced loads (no LDS staging or fragment reads for that operand)
# speedup vs baseline: 1.1463x; 1.0219x over previous
.LBB0_1154:
	s_or_b64 exec, exec, s[0:1]
	v_readlane_b32 s0, v253, 13
	v_lshrrev_b32_e32 v58, 4, v167
	v_readlane_b32 s1, v253, 14
	v_lshlrev_b32_e32 v120, 4, v201
	s_waitcnt vmcnt(1)
	v_and_b32_e32 v35, 15, v200
	s_andn2_b64 vcc, exec, s[0:1]
	v_lshlrev_b32_e32 v34, 3, v58
	v_lshlrev_b32_e32 v59, 3, v200
	s_waitcnt vmcnt(0)
	v_ashrrev_i32_e32 v37, 31, v120
	s_waitcnt lgkmcnt(0)
	s_barrier
	s_cbranch_vccnz .LBB0_1163
	s_movk_i32 s0, 0xfff
	v_cmp_lt_i32_e64 s[0:1], s0, v200
	v_lshl_or_b32 v2, v58, 2, v120
	v_or_b32_e32 v4, 16, v35
	v_writelane_b32 v251, s0, 20
	v_or_b32_e32 v5, 32, v35
	v_or_b32_e32 v6, 48, v35
	v_writelane_b32 v251, s1, 21
	v_cmp_ge_i32_e64 s[0:1], v2, v35
	v_or_b32_e32 v7, 64, v35
	v_or_b32_e32 v8, 0x50, v35
	v_writelane_b32 v251, s0, 18
	v_or_b32_e32 v9, 0x60, v35
	v_or_b32_e32 v10, 0x70, v35
	v_writelane_b32 v251, s1, 19
	v_cmp_ge_i32_e64 s[0:1], v35, v2
	v_or_b32_e32 v12, 1, v2
	v_add_u32_e32 v13, 0xffffff82, v2
	v_writelane_b32 v251, s0, 0
	v_add_u32_e32 v11, 0xffffff81, v2
	v_cvt_f32_i32_e32 v62, v12
	v_writelane_b32 v251, s1, 1
	v_cmp_ge_i32_e64 s[0:1], v2, v4
	v_cvt_f32_i32_e32 v63, v13
	v_lshlrev_b32_e32 v13, 7, v12
	v_writelane_b32 v251, s0, 58
	v_add_u32_e32 v14, 0xffffff83, v2
	v_cvt_f32_i32_e32 v60, v2
	v_writelane_b32 v251, s1, 59
	v_cmp_ge_i32_e64 s[0:1], v4, v2
	v_cvt_f32_i32_e32 v61, v11
	v_lshlrev_b32_e32 v11, 7, v2
	v_writelane_b32 v252, s0, 0
	v_cmp_gt_i32_e64 s[92:93], v10, v2
	v_cvt_f32_i32_e32 v65, v14
	v_writelane_b32 v252, s1, 1
	v_cmp_ge_i32_e64 s[0:1], v2, v5
	v_lshl_add_u32 v0, v58, 4, 16
	v_mul_u32_u24_e32 v3, 0x210, v35
	v_writelane_b32 v254, s0, 17
	s_waitcnt vmcnt(0)
	v_or_b32_e32 v38, v35, v11
	v_or_b32_e32 v40, v35, v13
	v_writelane_b32 v254, s1, 18
	v_cmp_ge_i32_e64 s[0:1], v5, v2
	v_readlane_b32 s70, v252, 21
	v_or_b32_e32 v36, v120, v35
	v_writelane_b32 v254, s0, 19
	v_ashrrev_i32_e32 v39, 31, v38
	v_ashrrev_i32_e32 v41, 31, v40
	v_writelane_b32 v254, s1, 20
	v_cmp_ge_i32_e64 s[0:1], v2, v6
	v_ashrrev_i32_e32 v47, 31, v11
	v_mov_b32_e32 v46, v38
	v_writelane_b32 v254, s0, 21
	v_ashrrev_i32_e32 v49, 31, v13
	v_mov_b32_e32 v48, v40
	v_writelane_b32 v254, s1, 22
	v_cmp_ge_i32_e64 s[0:1], v6, v2
	v_lshlrev_b32_e32 v54, 1, v34
	v_add_u32_e32 v68, v0, v3
	v_writelane_b32 v254, s0, 23
	s_mov_b32 s89, s70
	v_readlane_b32 s71, v252, 22
	v_writelane_b32 v254, s1, 24
	v_cmp_ge_i32_e64 s[0:1], v2, v7
	s_nop 1
	v_writelane_b32 v254, s0, 25
	s_nop 1
	v_writelane_b32 v254, s1, 26
	v_cmp_ge_i32_e64 s[0:1], v7, v2
	s_nop 1
	v_writelane_b32 v254, s0, 27
	s_nop 1
	v_writelane_b32 v254, s1, 28
	v_cmp_ge_i32_e64 s[0:1], v2, v8
	s_nop 1
	v_writelane_b32 v254, s0, 29
	s_nop 1
	v_writelane_b32 v254, s1, 30
	v_cmp_ge_i32_e64 s[0:1], v8, v2
	s_nop 1
	v_writelane_b32 v254, s0, 31
	s_nop 1
	v_writelane_b32 v254, s1, 32
	v_cmp_ge_i32_e64 s[0:1], v2, v9
	s_nop 1
	v_writelane_b32 v254, s0, 33
	s_nop 1
	v_writelane_b32 v254, s1, 34
	v_cmp_ge_i32_e64 s[0:1], v9, v2
	s_nop 1
	v_writelane_b32 v254, s0, 35
	s_nop 1
	v_writelane_b32 v254, s1, 36
	v_cmp_ge_i32_e64 s[0:1], v2, v10
	s_nop 1
	v_writelane_b32 v254, s0, 37
	s_nop 1
	v_writelane_b32 v254, s1, 38
	v_cmp_ge_i32_e64 s[0:1], v10, v2
	s_nop 1
	v_writelane_b32 v254, s0, 39
	s_nop 1
	v_writelane_b32 v254, s1, 40
	v_cmp_ge_i32_e64 s[0:1], v12, v35
	s_nop 1
	v_writelane_b32 v254, s0, 41
	s_nop 1
	v_writelane_b32 v254, s1, 42
	v_cmp_gt_i32_e64 s[0:1], v35, v2
	s_nop 1
	v_writelane_b32 v254, s0, 43
	s_nop 1
	v_writelane_b32 v254, s1, 44
	v_cmp_ge_i32_e64 s[0:1], v12, v4
	s_nop 1
	v_writelane_b32 v254, s0, 45
	s_nop 1
	v_writelane_b32 v254, s1, 46
	v_cmp_gt_i32_e64 s[0:1], v4, v2
	s_nop 1
	v_writelane_b32 v254, s0, 47
	s_nop 1
	v_writelane_b32 v254, s1, 48
	v_cmp_ge_i32_e64 s[0:1], v12, v5
	s_nop 1
	v_writelane_b32 v254, s0, 49
	s_nop 1
	v_writelane_b32 v254, s1, 50
	v_cmp_gt_i32_e64 s[0:1], v5, v2
	s_nop 1
	v_writelane_b32 v254, s0, 51
	s_nop 1
	v_writelane_b32 v254, s1, 52
	v_cmp_ge_i32_e64 s[0:1], v12, v6
	s_nop 1
	v_writelane_b32 v254, s0, 53
	s_nop 1
	v_writelane_b32 v254, s1, 54
	v_cmp_gt_i32_e64 s[0:1], v6, v2
	s_nop 1
	v_writelane_b32 v254, s0, 55
	s_nop 1
	v_writelane_b32 v254, s1, 56
	v_cmp_ge_i32_e64 s[0:1], v12, v7
	s_nop 1
	v_writelane_b32 v254, s0, 57
	s_nop 1
	v_writelane_b32 v254, s1, 58
	v_cmp_gt_i32_e64 s[0:1], v7, v2
	s_nop 1
	v_writelane_b32 v254, s0, 59
	s_nop 1
	v_writelane_b32 v254, s1, 60
	v_cmp_ge_i32_e64 s[0:1], v12, v8
	s_nop 1
	v_writelane_b32 v254, s0, 61
	s_nop 1
	v_writelane_b32 v254, s1, 62
	v_cmp_gt_i32_e64 s[0:1], v8, v2
	s_nop 1
	v_writelane_b32 v254, s0, 63
	s_nop 1
	v_writelane_b32 v255, s1, 0
	v_cmp_ge_i32_e64 s[0:1], v12, v9
	s_nop 1
	v_writelane_b32 v255, s0, 1
	s_nop 1
	v_writelane_b32 v255, s1, 2
	v_cmp_gt_i32_e64 s[0:1], v9, v2
	s_nop 1
	v_writelane_b32 v255, s0, 3
	s_nop 1
	v_writelane_b32 v255, s1, 4
	v_cmp_ge_i32_e64 s[0:1], v12, v10
	v_or_b32_e32 v12, 2, v2
	v_cvt_f32_i32_e32 v64, v12
	v_writelane_b32 v255, s0, 5
	v_lshlrev_b32_e32 v14, 7, v12
	v_cmp_ge_i32_e64 s[94:95], v12, v35
	v_writelane_b32 v255, s1, 6
	v_cmp_ge_i32_e64 s[96:97], v35, v12
	v_cmp_ge_i32_e64 s[6:7], v12, v4
	v_cmp_ge_i32_e64 s[16:17], v4, v12
	v_cmp_ge_i32_e64 s[18:19], v12, v5
	v_cmp_ge_i32_e64 s[20:21], v5, v12
	v_cmp_ge_i32_e64 s[22:23], v12, v6
	v_cmp_ge_i32_e64 s[24:25], v6, v12
	v_cmp_ge_i32_e64 s[26:27], v12, v7
	v_cmp_ge_i32_e64 s[28:29], v7, v12
	v_cmp_ge_i32_e64 s[30:31], v12, v8
	v_cmp_ge_i32_e64 s[34:35], v8, v12
	v_cmp_ge_i32_e64 s[36:37], v12, v9
	v_cmp_ge_i32_e64 s[0:1], v9, v12
	v_cmp_ge_i32_e64 s[2:3], v12, v10
	v_cmp_ge_i32_e64 s[4:5], v10, v12
	v_or_b32_e32 v12, 3, v2
	v_add_u32_e32 v2, 0xffffff84, v2
	v_cvt_f32_i32_e32 v66, v12
	v_cvt_f32_i32_e32 v67, v2
	v_lshlrev_b32_e32 v2, 7, v12
	v_or_b32_e32 v42, v35, v14
	v_or_b32_e32 v44, v35, v2
	v_ashrrev_i32_e32 v43, 31, v42
	v_cmp_ge_i32_e64 s[38:39], v12, v35
	v_cmp_ge_i32_e64 s[40:41], v35, v12
	v_ashrrev_i32_e32 v45, 31, v44
	v_cmp_ge_i32_e64 s[42:43], v12, v4
	v_cmp_ge_i32_e64 s[44:45], v4, v12
	v_cmp_ge_i32_e64 s[46:47], v12, v5
	v_cmp_ge_i32_e64 s[48:49], v5, v12
	v_cmp_ge_i32_e64 s[50:51], v12, v6
	v_cmp_ge_i32_e64 s[52:53], v6, v12
	v_cmp_ge_i32_e64 s[54:55], v12, v7
	v_cmp_ge_i32_e64 s[56:57], v7, v12
	v_cmp_ge_i32_e64 s[58:59], v12, v8
	v_cmp_ge_i32_e64 s[60:61], v8, v12
	v_cmp_ge_i32_e64 s[62:63], v12, v9
	v_cmp_ge_i32_e64 s[64:65], v9, v12
	v_cmp_ge_i32_e64 s[66:67], v12, v10
	v_cmp_ge_i32_e64 s[68:69], v10, v12
	v_ashrrev_i32_e32 v51, 31, v14
	v_mov_b32_e32 v50, v42
	v_ashrrev_i32_e32 v53, 31, v2
	v_mov_b32_e32 v52, v44
	v_mbcnt_lo_u32_b32 v56, -1, 0
	v_mbcnt_hi_u32_b32 v56, -1, v56
	v_lshrrev_b32_e32 v57, 4, v56
	v_mul_u32_u24_e32 v57, 0x1e0, v57
	v_lshrrev_b32_e32 v56, 3, v35
	v_mul_u32_u24_e32 v56, 0x78, v56
	v_sub_u32_e32 v56, v56, v57
	v_add_u32_e32 v38, v38, v56
	v_add_u32_e32 v46, v46, v56
	v_add_u32_e32 v40, v40, v56
	v_add_u32_e32 v40, 0xffffff88, v40
	v_add_u32_e32 v48, v48, v56
	v_add_u32_e32 v48, 0xffffff88, v48
	v_add_u32_e32 v42, v42, v56
	v_add_u32_e32 v42, 0xffffff10, v42
	v_add_u32_e32 v50, v50, v56
	v_add_u32_e32 v50, 0xffffff10, v50
	v_add_u32_e32 v44, v44, v56
	v_add_u32_e32 v44, 0xfffffe98, v44
	v_add_u32_e32 v52, v52, v56
	v_add_u32_e32 v52, 0xfffffe98, v52
	s_branch .LBB0_1157
.LBB0_1156:
	s_or_b64 exec, exec, s[78:79]
	s_lshl_b64 s[72:73], s[76:77], 24
	v_readlane_b32 s8, v251, 38
	v_lshl_add_u64 v[4:5], v[36:37], 0, v[4:5]
	v_readlane_b32 s9, v251, 39
	s_add_u32 s72, s8, s72
	v_lshlrev_b64 v[4:5], 11, v[4:5]
	s_addc_u32 s73, s9, s73
	v_lshl_add_u64 v[4:5], s[72:73], 0, v[4:5]
	v_lshl_add_u64 v[2:3], v[2:3], 1, v[4:5]
	v_mov_b32_e32 v55, v1
	v_lshl_add_u64 v[2:3], v[2:3], 0, v[54:55]
	s_waitcnt vmcnt(0)
	v_mul_f32_e32 v0, 0x3fb8aa3b, v6
	s_waitcnt lgkmcnt(0)
	s_barrier
	global_load_dwordx4 v[4:7], v[2:3], off
	ds_read_b128 v[8:11], v68
	ds_read_b128 v[78:81], v68 offset:64
	ds_read_b128 v[12:15], v68 offset:8448
	ds_read_b128 v[16:19], v68 offset:16896
	ds_read_b128 v[20:23], v68 offset:25344
	ds_read_b128 v[24:27], v68 offset:33792
	ds_read_b128 v[28:31], v68 offset:42240
	ds_read_b128 v[70:73], v68 offset:50688
	ds_read_b128 v[74:77], v68 offset:59136
	s_lshl_b64 s[70:71], s[70:71], 21
	v_readlane_b32 s8, v252, 26
	v_readlane_b32 s9, v252, 27
	s_add_u32 s70, s8, s70
	v_exp_f32_e32 v0, v0
	s_addc_u32 s71, s9, s71
	s_lshl_b32 s72, s90, 15
	s_add_u32 s76, s70, s72
	s_addc_u32 s77, s71, 0
	s_cmpk_lt_u32 s89, 0x100
	s_cselect_b64 s[70:71], -1, 0
	v_mul_f32_e32 v55, v0, v60
	v_mul_f32_e64 v56, -v0, v61
	v_readlane_b32 s8, v251, 18
	v_cndmask_b32_e64 v55, v55, v56, s[70:71]
	v_readlane_b32 s9, v251, 19
	v_mul_f32_e32 v55, 0x3fb8aa3b, v55
	v_exp_f32_e32 v55, v55
	v_cndmask_b32_e64 v56, 0, 1, s[8:9]
	v_readlane_b32 s8, v251, 0
	v_readlane_b32 s9, v251, 1
	s_waitcnt vmcnt(0) lgkmcnt(8)
	v_mfma_f32_16x16x32_bf16 v[8:11], v[4:7], v[8:11], 0
	v_cndmask_b32_e64 v57, 0, 1, s[8:9]
	v_cndmask_b32_e64 v56, v57, v56, s[70:71]
	v_and_b32_e32 v56, 1, v56
	s_waitcnt lgkmcnt(6)
	v_mfma_f32_16x16x32_bf16 v[12:15], v[4:7], v[12:15], 0
	v_cmp_eq_u32_e32 vcc, 1, v56
	v_readlane_b32 s8, v251, 58
	v_readlane_b32 s9, v251, 59
	s_waitcnt lgkmcnt(5)
	v_mfma_f32_16x16x32_bf16 v[16:19], v[4:7], v[16:19], 0
	s_waitcnt lgkmcnt(4)
	v_mfma_f32_16x16x32_bf16 v[20:23], v[4:7], v[20:23], 0
	s_waitcnt lgkmcnt(3)
	v_mfma_f32_16x16x32_bf16 v[24:27], v[4:7], v[24:27], 0
	s_waitcnt lgkmcnt(2)
	v_mfma_f32_16x16x32_bf16 v[28:31], v[4:7], v[28:31], 0
	s_waitcnt lgkmcnt(1)
	v_mfma_f32_16x16x32_bf16 v[70:73], v[4:7], v[70:73], 0
	s_waitcnt lgkmcnt(0)
	v_mfma_f32_16x16x32_bf16 v[4:7], v[4:7], v[74:77], 0
	global_load_dwordx4 v[74:77], v[2:3], off offset:64
	s_waitcnt vmcnt(0)
	v_mfma_f32_16x16x32_bf16 v[8:11], v[74:77], v[78:81], v[8:11]
	ds_read_b128 v[78:81], v68 offset:8512
	s_waitcnt lgkmcnt(0)
	v_mfma_f32_16x16x32_bf16 v[12:15], v[74:77], v[78:81], v[12:15]
	ds_read_b128 v[78:81], v68 offset:16960
	s_waitcnt lgkmcnt(0)
	v_mfma_f32_16x16x32_bf16 v[16:19], v[74:77], v[78:81], v[16:19]
	ds_read_b128 v[78:81], v68 offset:25408
	s_waitcnt lgkmcnt(0)
	v_mfma_f32_16x16x32_bf16 v[20:23], v[74:77], v[78:81], v[20:23]
	ds_read_b128 v[78:81], v68 offset:33856
	s_waitcnt lgkmcnt(0)
	v_mfma_f32_16x16x32_bf16 v[24:27], v[74:77], v[78:81], v[24:27]
	ds_read_b128 v[78:81], v68 offset:42304
	s_waitcnt lgkmcnt(0)
	v_mfma_f32_16x16x32_bf16 v[28:31], v[74:77], v[78:81], v[28:31]
	ds_read_b128 v[78:81], v68 offset:50752
	s_waitcnt lgkmcnt(0)
	v_mfma_f32_16x16x32_bf16 v[70:73], v[74:77], v[78:81], v[70:73]
	ds_read_b128 v[78:81], v68 offset:59200
	s_waitcnt lgkmcnt(0)
	v_mfma_f32_16x16x32_bf16 v[4:7], v[74:77], v[78:81], v[4:7]
	global_load_dwordx4 v[74:77], v[2:3], off offset:128
	ds_read_b128 v[78:81], v68 offset:128
	s_waitcnt vmcnt(0) lgkmcnt(0)
	v_mfma_f32_16x16x32_bf16 v[8:11], v[74:77], v[78:81], v[8:11]
	ds_read_b128 v[78:81], v68 offset:8576
	s_waitcnt lgkmcnt(0)
	v_mfma_f32_16x16x32_bf16 v[12:15], v[74:77], v[78:81], v[12:15]
	ds_read_b128 v[78:81], v68 offset:17024
	s_waitcnt lgkmcnt(0)
	v_mfma_f32_16x16x32_bf16 v[16:19], v[74:77], v[78:81], v[16:19]
	ds_read_b128 v[78:81], v68 offset:25472
	s_waitcnt lgkmcnt(0)
	v_mfma_f32_16x16x32_bf16 v[20:23], v[74:77], v[78:81], v[20:23]
	ds_read_b128 v[78:81], v68 offset:33920
	s_waitcnt lgkmcnt(0)
	v_mfma_f32_16x16x32_bf16 v[24:27], v[74:77], v[78:81], v[24:27]
	ds_read_b128 v[78:81], v68 offset:42368
	s_waitcnt lgkmcnt(0)
	v_mfma_f32_16x16x32_bf16 v[28:31], v[74:77], v[78:81], v[28:31]
	ds_read_b128 v[78:81], v68 offset:50816
	s_waitcnt lgkmcnt(0)
	v_mfma_f32_16x16x32_bf16 v[70:73], v[74:77], v[78:81], v[70:73]
	ds_read_b128 v[78:81], v68 offset:59264
	s_waitcnt lgkmcnt(0)
	v_mfma_f32_16x16x32_bf16 v[4:7], v[74:77], v[78:81], v[4:7]
	global_load_dwordx4 v[74:77], v[2:3], off offset:192
	ds_read_b128 v[78:81], v68 offset:192
	s_waitcnt vmcnt(0) lgkmcnt(0)
	v_mfma_f32_16x16x32_bf16 v[8:11], v[74:77], v[78:81], v[8:11]
	ds_read_b128 v[78:81], v68 offset:8640
	s_waitcnt lgkmcnt(0)
	v_mfma_f32_16x16x32_bf16 v[12:15], v[74:77], v[78:81], v[12:15]
	ds_read_b128 v[78:81], v68 offset:17088
	s_waitcnt lgkmcnt(0)
	v_mfma_f32_16x16x32_bf16 v[16:19], v[74:77], v[78:81], v[16:19]
	ds_read_b128 v[78:81], v68 offset:25536
	s_waitcnt lgkmcnt(0)
	v_mfma_f32_16x16x32_bf16 v[20:23], v[74:77], v[78:81], v[20:23]
	ds_read_b128 v[78:81], v68 offset:33984
	s_waitcnt lgkmcnt(0)
	v_mfma_f32_16x16x32_bf16 v[24:27], v[74:77], v[78:81], v[24:27]
	ds_read_b128 v[78:81], v68 offset:42432
	s_waitcnt lgkmcnt(0)
	v_mfma_f32_16x16x32_bf16 v[28:31], v[74:77], v[78:81], v[28:31]
	ds_read_b128 v[78:81], v68 offset:50880
	s_waitcnt lgkmcnt(0)
	v_mfma_f32_16x16x32_bf16 v[70:73], v[74:77], v[78:81], v[70:73]
	ds_read_b128 v[78:81], v68 offset:59328
	s_waitcnt lgkmcnt(0)
	v_mfma_f32_16x16x32_bf16 v[4:7], v[74:77], v[78:81], v[4:7]
	global_load_dwordx4 v[74:77], v[2:3], off offset:256
	ds_read_b128 v[78:81], v68 offset:256
	s_waitcnt vmcnt(0) lgkmcnt(0)
	v_mfma_f32_16x16x32_bf16 v[8:11], v[74:77], v[78:81], v[8:11]
	ds_read_b128 v[78:81], v68 offset:8704
	s_waitcnt lgkmcnt(0)
	v_mfma_f32_16x16x32_bf16 v[12:15], v[74:77], v[78:81], v[12:15]
	ds_read_b128 v[78:81], v68 offset:17152
	s_waitcnt lgkmcnt(0)
	v_mfma_f32_16x16x32_bf16 v[16:19], v[74:77], v[78:81], v[16:19]
	ds_read_b128 v[78:81], v68 offset:25600
	s_waitcnt lgkmcnt(0)
	v_mfma_f32_16x16x32_bf16 v[20:23], v[74:77], v[78:81], v[20:23]
	ds_read_b128 v[78:81], v68 offset:34048
	s_waitcnt lgkmcnt(0)
	v_mfma_f32_16x16x32_bf16 v[24:27], v[74:77], v[78:81], v[24:27]
	ds_read_b128 v[78:81], v68 offset:42496
	s_waitcnt lgkmcnt(0)
	v_mfma_f32_16x16x32_bf16 v[28:31], v[74:77], v[78:81], v[28:31]
	ds_read_b128 v[78:81], v68 offset:50944
	s_waitcnt lgkmcnt(0)
	v_mfma_f32_16x16x32_bf16 v[70:73], v[74:77], v[78:81], v[70:73]
	ds_read_b128 v[78:81], v68 offset:59392
	s_waitcnt lgkmcnt(0)
	v_mfma_f32_16x16x32_bf16 v[4:7], v[74:77], v[78:81], v[4:7]
	global_load_dwordx4 v[74:77], v[2:3], off offset:320
	ds_read_b128 v[78:81], v68 offset:320
	s_waitcnt vmcnt(0) lgkmcnt(0)
	v_mfma_f32_16x16x32_bf16 v[8:11], v[74:77], v[78:81], v[8:11]
	ds_read_b128 v[78:81], v68 offset:8768
	s_waitcnt lgkmcnt(0)
	v_mfma_f32_16x16x32_bf16 v[12:15], v[74:77], v[78:81], v[12:15]
	ds_read_b128 v[78:81], v68 offset:17216
	s_waitcnt lgkmcnt(0)
	v_mfma_f32_16x16x32_bf16 v[16:19], v[74:77], v[78:81], v[16:19]
	ds_read_b128 v[78:81], v68 offset:25664
	s_waitcnt lgkmcnt(0)
	v_mfma_f32_16x16x32_bf16 v[20:23], v[74:77], v[78:81], v[20:23]
	ds_read_b128 v[78:81], v68 offset:34112
	s_waitcnt lgkmcnt(0)
	v_mfma_f32_16x16x32_bf16 v[24:27], v[74:77], v[78:81], v[24:27]
	ds_read_b128 v[78:81], v68 offset:42560
	s_waitcnt lgkmcnt(0)
	v_mfma_f32_16x16x32_bf16 v[28:31], v[74:77], v[78:81], v[28:31]
	ds_read_b128 v[78:81], v68 offset:51008
	s_waitcnt lgkmcnt(0)
	v_mfma_f32_16x16x32_bf16 v[70:73], v[74:77], v[78:81], v[70:73]
	ds_read_b128 v[78:81], v68 offset:59456
	s_waitcnt lgkmcnt(0)
	v_mfma_f32_16x16x32_bf16 v[4:7], v[74:77], v[78:81], v[4:7]
	global_load_dwordx4 v[74:77], v[2:3], off offset:384
	ds_read_b128 v[78:81], v68 offset:384
	s_waitcnt vmcnt(0) lgkmcnt(0)
	v_mfma_f32_16x16x32_bf16 v[8:11], v[74:77], v[78:81], v[8:11]
	ds_read_b128 v[78:81], v68 offset:8832
	s_waitcnt lgkmcnt(0)
	v_mfma_f32_16x16x32_bf16 v[12:15], v[74:77], v[78:81], v[12:15]
	ds_read_b128 v[78:81], v68 offset:17280
	s_waitcnt lgkmcnt(0)
	v_mfma_f32_16x16x32_bf16 v[16:19], v[74:77], v[78:81], v[16:19]
	ds_read_b128 v[78:81], v68 offset:25728
	s_waitcnt lgkmcnt(0)
	v_mfma_f32_16x16x32_bf16 v[78:81], v[74:77], v[78:81], v[20:23]
	s_nop 2
	ds_read_b128 v[20:23], v68 offset:34176
	s_waitcnt lgkmcnt(0)
	v_mfma_f32_16x16x32_bf16 v[82:85], v[74:77], v[20:23], v[24:27]
	ds_read_b128 v[20:23], v68 offset:42624
	s_waitcnt lgkmcnt(0)
	v_mfma_f32_16x16x32_bf16 v[86:89], v[74:77], v[20:23], v[28:31]
	ds_read_b128 v[20:23], v68 offset:51072
	s_waitcnt lgkmcnt(0)
	v_mfma_f32_16x16x32_bf16 v[70:73], v[74:77], v[20:23], v[70:73]
	ds_read_b128 v[20:23], v68 offset:59520
	s_waitcnt lgkmcnt(0)
	v_mfma_f32_16x16x32_bf16 v[74:77], v[74:77], v[20:23], v[4:7]
	ds_read_b128 v[20:23], v68 offset:448
	s_nop 1
	global_load_dwordx4 v[2:5], v[2:3], off offset:448
	s_waitcnt vmcnt(0) lgkmcnt(0)
	v_mfma_f32_16x16x32_bf16 v[30:33], v[2:5], v[20:23], v[8:11]
	s_nop 2
	ds_read_b128 v[6:9], v68 offset:8896
	s_nop 3
	v_mul_f32_e32 v30, v55, v30
	v_cndmask_b32_e32 v30, 0, v30, vcc
	v_bfe_u32 v56, v30, 16, 1
	v_add3_u32 v30, v30, v56, s33
	v_lshl_add_u64 v[56:57], v[38:39], 1, s[76:77]
	global_store_short_d16_hi v[56:57], v30, off
	v_cndmask_b32_e64 v30, 0, 1, s[8:9]
	v_readlane_b32 s8, v252, 0
	s_waitcnt lgkmcnt(0)
	v_mfma_f32_16x16x32_bf16 v[26:29], v[2:5], v[6:9], v[12:15]
	v_readlane_b32 s9, v252, 1
	ds_read_b128 v[6:9], v68 offset:17344
	s_nop 0
	v_cndmask_b32_e64 v56, 0, 1, s[8:9]
	v_cndmask_b32_e64 v30, v56, v30, s[70:71]
	v_and_b32_e32 v30, 1, v30
	v_cmp_eq_u32_e32 vcc, 1, v30
	s_nop 0
	v_mul_f32_e32 v26, v55, v26
	v_readlane_b32 s8, v254, 17
	v_cndmask_b32_e32 v26, 0, v26, vcc
	v_bfe_u32 v30, v26, 16, 1
	v_add3_u32 v26, v26, v30, s33
	v_lshl_add_u64 v[56:57], v[46:47], 1, s[76:77]
	v_readlane_b32 s9, v254, 18
	global_store_short_d16_hi v[56:57], v26, off offset:512
	s_waitcnt lgkmcnt(0)
	v_mfma_f32_16x16x32_bf16 v[22:25], v[2:5], v[6:9], v[16:19]
	v_cndmask_b32_e64 v26, 0, 1, s[8:9]
	v_readlane_b32 s8, v254, 19
	v_readlane_b32 s9, v254, 20
	ds_read_b128 v[6:9], v68 offset:25792
	s_waitcnt lgkmcnt(0)
	v_mfma_f32_16x16x32_bf16 v[18:21], v[2:5], v[6:9], v[78:81]
	v_cndmask_b32_e64 v30, 0, 1, s[8:9]
	v_cndmask_b32_e64 v26, v30, v26, s[70:71]
	v_and_b32_e32 v26, 1, v26
	v_cmp_eq_u32_e32 vcc, 1, v26
	v_mul_f32_e32 v22, v55, v22
	v_readlane_b32 s8, v254, 21
	v_cndmask_b32_e32 v22, 0, v22, vcc
	v_bfe_u32 v26, v22, 16, 1
	v_add3_u32 v22, v22, v26, s33
	v_readlane_b32 s9, v254, 22
	global_store_short_d16_hi v[56:57], v22, off offset:1024
	ds_read_b128 v[6:9], v68 offset:34240
	v_cndmask_b32_e64 v22, 0, 1, s[8:9]
	v_readlane_b32 s8, v254, 23
	v_readlane_b32 s9, v254, 24
	v_mul_f32_e32 v18, v55, v18
	s_waitcnt lgkmcnt(0)
	v_mfma_f32_16x16x32_bf16 v[14:17], v[2:5], v[6:9], v[82:85]
	v_cndmask_b32_e64 v26, 0, 1, s[8:9]
	v_cndmask_b32_e64 v22, v26, v22, s[70:71]
	v_and_b32_e32 v22, 1, v22
	v_cmp_eq_u32_e32 vcc, 1, v22
	v_readlane_b32 s8, v254, 25
	v_readlane_b32 s9, v254, 26
	v_cndmask_b32_e32 v18, 0, v18, vcc
	v_bfe_u32 v22, v18, 16, 1
	v_add3_u32 v18, v18, v22, s33
	global_store_short_d16_hi v[56:57], v18, off offset:1536
	v_cndmask_b32_e64 v18, 0, 1, s[8:9]
	v_readlane_b32 s8, v254, 27
	v_readlane_b32 s9, v254, 28
	ds_read_b128 v[6:9], v68 offset:42688
	v_mul_f32_e32 v14, v55, v14
	v_cndmask_b32_e64 v22, 0, 1, s[8:9]
	v_cndmask_b32_e64 v18, v22, v18, s[70:71]
	v_and_b32_e32 v18, 1, v18
	v_cmp_eq_u32_e32 vcc, 1, v18
	v_readlane_b32 s8, v254, 29
	v_readlane_b32 s9, v254, 30
	v_cndmask_b32_e32 v14, 0, v14, vcc
	v_bfe_u32 v18, v14, 16, 1
	v_add3_u32 v14, v14, v18, s33
	global_store_short_d16_hi v[56:57], v14, off offset:2048
	v_cndmask_b32_e64 v14, 0, 1, s[8:9]
	v_readlane_b32 s8, v254, 31
	s_waitcnt lgkmcnt(0)
	v_mfma_f32_16x16x32_bf16 v[10:13], v[2:5], v[6:9], v[86:89]
	v_readlane_b32 s9, v254, 32
	ds_read_b128 v[6:9], v68 offset:51136
	s_nop 0
	v_cndmask_b32_e64 v18, 0, 1, s[8:9]
	v_cndmask_b32_e64 v14, v18, v14, s[70:71]
	v_and_b32_e32 v14, 1, v14
	v_cmp_eq_u32_e32 vcc, 1, v14
	s_nop 0
	v_mul_f32_e32 v10, v55, v10
	v_readlane_b32 s8, v254, 33
	v_cndmask_b32_e32 v10, 0, v10, vcc
	v_bfe_u32 v14, v10, 16, 1
	v_add3_u32 v10, v10, v14, s33
	v_readlane_b32 s9, v254, 34
	global_store_short_d16_hi v[56:57], v10, off offset:2560
	s_waitcnt lgkmcnt(0)
	v_mfma_f32_16x16x32_bf16 v[6:9], v[2:5], v[6:9], v[70:73]
	v_cndmask_b32_e64 v10, 0, 1, s[8:9]
	v_readlane_b32 s8, v254, 35
	v_readlane_b32 s9, v254, 36
	ds_read_b128 v[70:73], v68 offset:59584
	s_waitcnt lgkmcnt(0)
	v_mfma_f32_16x16x32_bf16 v[2:5], v[2:5], v[70:73], v[74:77]
	v_cndmask_b32_e64 v14, 0, 1, s[8:9]
	v_cndmask_b32_e64 v10, v14, v10, s[70:71]
	v_and_b32_e32 v10, 1, v10
	v_cmp_eq_u32_e32 vcc, 1, v10
	v_mul_f32_e32 v6, v55, v6
	v_readlane_b32 s8, v254, 37
	v_cndmask_b32_e32 v6, 0, v6, vcc
	v_bfe_u32 v10, v6, 16, 1
	v_add3_u32 v6, v6, v10, s33
	v_readlane_b32 s9, v254, 38
	global_store_short_d16_hi v[56:57], v6, off offset:3072
	v_mul_f32_e32 v2, v55, v2
	v_cndmask_b32_e64 v6, 0, 1, s[8:9]
	v_readlane_b32 s8, v254, 39
	v_readlane_b32 s9, v254, 40
	s_nop 1
	v_cndmask_b32_e64 v10, 0, 1, s[8:9]
	v_cndmask_b32_e64 v6, v10, v6, s[70:71]
	v_and_b32_e32 v6, 1, v6
	v_cmp_eq_u32_e32 vcc, 1, v6
	v_readlane_b32 s8, v254, 41
	v_readlane_b32 s9, v254, 42
	v_cndmask_b32_e32 v2, 0, v2, vcc
	v_bfe_u32 v6, v2, 16, 1
	v_add3_u32 v2, v2, v6, s33
	global_store_short_d16_hi v[56:57], v2, off offset:3584
	v_mul_f32_e64 v2, -v0, v63
	v_mul_f32_e32 v6, v0, v62
	v_cndmask_b32_e64 v2, v6, v2, s[70:71]
	v_mul_f32_e32 v2, 0x3fb8aa3b, v2
	v_cndmask_b32_e64 v6, 0, 1, s[8:9]
	v_readlane_b32 s8, v254, 43
	v_exp_f32_e32 v2, v2
	v_readlane_b32 s9, v254, 44
	s_nop 1
	v_cndmask_b32_e64 v10, 0, 1, s[8:9]
	v_cndmask_b32_e64 v6, v10, v6, s[70:71]
	v_and_b32_e32 v6, 1, v6
	v_cmp_eq_u32_e32 vcc, 1, v6
	v_mul_f32_e32 v6, v2, v31
	v_readlane_b32 s8, v254, 45
	v_cndmask_b32_e32 v6, 0, v6, vcc
	v_bfe_u32 v10, v6, 16, 1
	v_add3_u32 v6, v6, v10, s33
	v_lshl_add_u64 v[30:31], v[40:41], 1, s[76:77]
	v_readlane_b32 s9, v254, 46
	global_store_short_d16_hi v[30:31], v6, off
	s_nop 0
	v_cndmask_b32_e64 v6, 0, 1, s[8:9]
	v_readlane_b32 s8, v254, 47
	v_readlane_b32 s9, v254, 48
	s_nop 1
	v_cndmask_b32_e64 v10, 0, 1, s[8:9]
	v_cndmask_b32_e64 v6, v10, v6, s[70:71]
	v_and_b32_e32 v6, 1, v6
	v_cmp_eq_u32_e32 vcc, 1, v6
	v_mul_f32_e32 v6, v2, v27
	v_readlane_b32 s8, v254, 49
	v_cndmask_b32_e32 v6, 0, v6, vcc
	v_bfe_u32 v10, v6, 16, 1
	v_add3_u32 v6, v6, v10, s33
	v_lshl_add_u64 v[26:27], v[48:49], 1, s[76:77]
	v_readlane_b32 s9, v254, 50
	global_store_short_d16_hi v[26:27], v6, off offset:512
	s_nop 0
	v_cndmask_b32_e64 v6, 0, 1, s[8:9]
	v_readlane_b32 s8, v254, 51
	v_readlane_b32 s9, v254, 52
	s_nop 1
	v_cndmask_b32_e64 v10, 0, 1, s[8:9]
	v_cndmask_b32_e64 v6, v10, v6, s[70:71]
	v_and_b32_e32 v6, 1, v6
	v_cmp_eq_u32_e32 vcc, 1, v6
	v_mul_f32_e32 v6, v2, v23
	v_readlane_b32 s8, v254, 53
	v_cndmask_b32_e32 v6, 0, v6, vcc
	v_bfe_u32 v10, v6, 16, 1
	v_add3_u32 v6, v6, v10, s33
	v_readlane_b32 s9, v254, 54
	global_store_short_d16_hi v[26:27], v6, off offset:1024
	s_nop 0
	v_cndmask_b32_e64 v6, 0, 1, s[8:9]
	v_readlane_b32 s8, v254, 55
	v_readlane_b32 s9, v254, 56
	s_nop 1
	v_cndmask_b32_e64 v10, 0, 1, s[8:9]
	v_cndmask_b32_e64 v6, v10, v6, s[70:71]
	v_and_b32_e32 v6, 1, v6
	v_cmp_eq_u32_e32 vcc, 1, v6
	v_mul_f32_e32 v6, v2, v19
	v_readlane_b32 s8, v254, 57
	v_cndmask_b32_e32 v6, 0, v6, vcc
	v_bfe_u32 v10, v6, 16, 1
	v_add3_u32 v6, v6, v10, s33
	v_readlane_b32 s9, v254, 58
	global_store_short_d16_hi v[26:27], v6, off offset:1536
	s_nop 0
	v_cndmask_b32_e64 v6, 0, 1, s[8:9]
	v_readlane_b32 s8, v254, 59
	v_readlane_b32 s9, v254, 60
	s_nop 1
	v_cndmask_b32_e64 v10, 0, 1, s[8:9]
	v_cndmask_b32_e64 v6, v10, v6, s[70:71]
	v_and_b32_e32 v6, 1, v6
	v_cmp_eq_u32_e32 vcc, 1, v6
	v_mul_f32_e32 v6, v2, v15
	v_readlane_b32 s8, v254, 61
	v_cndmask_b32_e32 v6, 0, v6, vcc
	v_bfe_u32 v10, v6, 16, 1
	v_add3_u32 v6, v6, v10, s33
	v_readlane_b32 s9, v254, 62
	global_store_short_d16_hi v[26:27], v6, off offset:2048
	s_nop 0
	v_cndmask_b32_e64 v6, 0, 1, s[8:9]
	v_readlane_b32 s8, v254, 63
	v_readlane_b32 s9, v255, 0
	s_nop 1
	v_cndmask_b32_e64 v10, 0, 1, s[8:9]
	v_cndmask_b32_e64 v6, v10, v6, s[70:71]
	v_and_b32_e32 v6, 1, v6
	v_cmp_eq_u32_e32 vcc, 1, v6
	v_mul_f32_e32 v6, v2, v11
	v_readlane_b32 s8, v255, 1
	v_cndmask_b32_e32 v6, 0, v6, vcc
	v_bfe_u32 v10, v6, 16, 1
	v_add3_u32 v6, v6, v10, s33
	v_readlane_b32 s9, v255, 2
	global_store_short_d16_hi v[26:27], v6, off offset:2560
	s_nop 0
	v_cndmask_b32_e64 v6, 0, 1, s[8:9]
	v_readlane_b32 s8, v255, 3
	v_readlane_b32 s9, v255, 4
	s_nop 1
	v_cndmask_b32_e64 v10, 0, 1, s[8:9]
	v_cndmask_b32_e64 v6, v10, v6, s[70:71]
	v_and_b32_e32 v6, 1, v6
	v_cmp_eq_u32_e32 vcc, 1, v6
	v_mul_f32_e32 v6, v2, v7
	v_readlane_b32 s8, v255, 5
	v_cndmask_b32_e32 v6, 0, v6, vcc
	v_bfe_u32 v7, v6, 16, 1
	v_add3_u32 v6, v6, v7, s33
	v_readlane_b32 s9, v255, 6
	global_store_short_d16_hi v[26:27], v6, off offset:3072
	v_cndmask_b32_e64 v7, 0, 1, s[92:93]
	v_cndmask_b32_e64 v6, 0, 1, s[8:9]
	v_cndmask_b32_e64 v6, v7, v6, s[70:71]
	v_and_b32_e32 v6, 1, v6
	v_cmp_eq_u32_e32 vcc, 1, v6
	v_mul_f32_e32 v2, v2, v3
	v_cndmask_b32_e64 v10, 0, 1, s[20:21]
	v_cndmask_b32_e32 v2, 0, v2, vcc
	v_bfe_u32 v3, v2, 16, 1
	v_add3_u32 v2, v2, v3, s33
	global_store_short_d16_hi v[26:27], v2, off offset:3584
	v_mul_f32_e64 v2, -v0, v65
	v_mul_f32_e32 v3, v0, v64
	v_cndmask_b32_e64 v2, v3, v2, s[70:71]
	v_mul_f32_e32 v2, 0x3fb8aa3b, v2
	v_exp_f32_e32 v6, v2
	v_cndmask_b32_e64 v2, 0, 1, s[94:95]
	v_cndmask_b32_e64 v3, 0, 1, s[96:97]
	v_cndmask_b32_e64 v2, v3, v2, s[70:71]
	v_and_b32_e32 v2, 1, v2
	v_cmp_eq_u32_e32 vcc, 1, v2
	v_mul_f32_e32 v2, v6, v32
	v_mul_f32_e32 v4, v6, v4
	v_cndmask_b32_e32 v2, 0, v2, vcc
	v_bfe_u32 v3, v2, 16, 1
	v_add3_u32 v7, v2, v3, s33
	v_lshl_add_u64 v[2:3], v[42:43], 1, s[76:77]
	global_store_short_d16_hi v[2:3], v7, off
	v_cndmask_b32_e64 v2, 0, 1, s[6:7]
	v_cndmask_b32_e64 v3, 0, 1, s[16:17]
	v_cndmask_b32_e64 v2, v3, v2, s[70:71]
	v_and_b32_e32 v2, 1, v2
	v_cmp_eq_u32_e32 vcc, 1, v2
	v_mul_f32_e32 v2, v6, v28
	s_nop 0
	v_cndmask_b32_e32 v2, 0, v2, vcc
	v_bfe_u32 v3, v2, 16, 1
	v_add3_u32 v7, v2, v3, s33
	v_lshl_add_u64 v[2:3], v[50:51], 1, s[76:77]
	global_store_short_d16_hi v[2:3], v7, off offset:512
	v_cndmask_b32_e64 v7, 0, 1, s[18:19]
	v_cndmask_b32_e64 v7, v10, v7, s[70:71]
	v_and_b32_e32 v7, 1, v7
	v_cmp_eq_u32_e32 vcc, 1, v7
	v_mul_f32_e32 v7, v6, v24
	s_nop 0
	v_cndmask_b32_e32 v7, 0, v7, vcc
	v_bfe_u32 v10, v7, 16, 1
	v_add3_u32 v7, v7, v10, s33
	global_store_short_d16_hi v[2:3], v7, off offset:1024
	v_cndmask_b32_e64 v7, 0, 1, s[22:23]
	v_cndmask_b32_e64 v10, 0, 1, s[24:25]
	v_cndmask_b32_e64 v7, v10, v7, s[70:71]
	v_and_b32_e32 v7, 1, v7
	v_cmp_eq_u32_e32 vcc, 1, v7
	v_mul_f32_e32 v7, v6, v20
	s_nop 0
	v_cndmask_b32_e32 v7, 0, v7, vcc
	v_bfe_u32 v10, v7, 16, 1
	v_add3_u32 v7, v7, v10, s33
	global_store_short_d16_hi v[2:3], v7, off offset:1536
	v_cndmask_b32_e64 v7, 0, 1, s[26:27]
	v_cndmask_b32_e64 v10, 0, 1, s[28:29]
	v_cndmask_b32_e64 v7, v10, v7, s[70:71]
	v_and_b32_e32 v7, 1, v7
	v_cmp_eq_u32_e32 vcc, 1, v7
	v_mul_f32_e32 v7, v6, v16
	s_nop 0
	v_cndmask_b32_e32 v7, 0, v7, vcc
	v_bfe_u32 v10, v7, 16, 1
	v_add3_u32 v7, v7, v10, s33
	global_store_short_d16_hi v[2:3], v7, off offset:2048
	v_cndmask_b32_e64 v7, 0, 1, s[30:31]
	v_cndmask_b32_e64 v10, 0, 1, s[34:35]
	v_cndmask_b32_e64 v7, v10, v7, s[70:71]
	v_and_b32_e32 v7, 1, v7
	v_cmp_eq_u32_e32 vcc, 1, v7
	v_mul_f32_e32 v7, v6, v12
	s_nop 0
	v_cndmask_b32_e32 v7, 0, v7, vcc
	v_bfe_u32 v10, v7, 16, 1
	v_add3_u32 v7, v7, v10, s33
	global_store_short_d16_hi v[2:3], v7, off offset:2560
	v_cndmask_b32_e64 v7, 0, 1, s[36:37]
	v_cndmask_b32_e64 v10, 0, 1, s[0:1]
	v_cndmask_b32_e64 v7, v10, v7, s[70:71]
	v_and_b32_e32 v7, 1, v7
	v_cmp_eq_u32_e32 vcc, 1, v7
	v_mul_f32_e32 v7, v6, v8
	s_nop 0
	v_cndmask_b32_e32 v7, 0, v7, vcc
	v_bfe_u32 v8, v7, 16, 1
	v_add3_u32 v7, v7, v8, s33
	global_store_short_d16_hi v[2:3], v7, off offset:3072
	v_cndmask_b32_e64 v7, 0, 1, s[2:3]
	v_cndmask_b32_e64 v8, 0, 1, s[4:5]
	v_cndmask_b32_e64 v7, v8, v7, s[70:71]
	v_and_b32_e32 v7, 1, v7
	v_cmp_eq_u32_e32 vcc, 1, v7
	s_nop 1
	v_cndmask_b32_e32 v4, 0, v4, vcc
	v_bfe_u32 v6, v4, 16, 1
	v_add3_u32 v4, v4, v6, s33
	global_store_short_d16_hi v[2:3], v4, off offset:3584
	v_mul_f32_e64 v2, -v0, v67
	v_mul_f32_e32 v0, v0, v66
	v_cndmask_b32_e64 v0, v0, v2, s[70:71]
	v_mul_f32_e32 v0, 0x3fb8aa3b, v0
	v_exp_f32_e32 v0, v0
	v_cndmask_b32_e64 v2, 0, 1, s[38:39]
	v_cndmask_b32_e64 v3, 0, 1, s[40:41]
	v_cndmask_b32_e64 v2, v3, v2, s[70:71]
	v_and_b32_e32 v2, 1, v2
	v_cmp_eq_u32_e32 vcc, 1, v2
	v_mul_f32_e32 v2, v0, v33
	v_cndmask_b32_e64 v6, 0, 1, s[48:49]
	v_cndmask_b32_e32 v2, 0, v2, vcc
	v_bfe_u32 v3, v2, 16, 1
	v_add3_u32 v4, v2, v3, s33
	v_lshl_add_u64 v[2:3], v[44:45], 1, s[76:77]
	global_store_short_d16_hi v[2:3], v4, off
	v_cndmask_b32_e64 v2, 0, 1, s[42:43]
	v_cndmask_b32_e64 v3, 0, 1, s[44:45]
	v_cndmask_b32_e64 v2, v3, v2, s[70:71]
	v_and_b32_e32 v2, 1, v2
	v_cmp_eq_u32_e32 vcc, 1, v2
	v_mul_f32_e32 v2, v0, v29
	s_nop 0
	v_cndmask_b32_e32 v2, 0, v2, vcc
	v_bfe_u32 v3, v2, 16, 1
	v_add3_u32 v4, v2, v3, s33
	v_lshl_add_u64 v[2:3], v[52:53], 1, s[76:77]
	global_store_short_d16_hi v[2:3], v4, off offset:512
	v_cndmask_b32_e64 v4, 0, 1, s[46:47]
	v_cndmask_b32_e64 v4, v6, v4, s[70:71]
	v_and_b32_e32 v4, 1, v4
	v_cmp_eq_u32_e32 vcc, 1, v4
	v_mul_f32_e32 v4, v0, v25
	v_readlane_b32 s76, v252, 17
	v_cndmask_b32_e32 v4, 0, v4, vcc
	v_bfe_u32 v6, v4, 16, 1
	v_add3_u32 v4, v4, v6, s33
	global_store_short_d16_hi v[2:3], v4, off offset:1024
	v_cndmask_b32_e64 v4, 0, 1, s[50:51]
	v_cndmask_b32_e64 v6, 0, 1, s[52:53]
	v_cndmask_b32_e64 v4, v6, v4, s[70:71]
	v_and_b32_e32 v4, 1, v4
	v_cmp_eq_u32_e32 vcc, 1, v4
	v_mul_f32_e32 v4, v0, v21
	v_readlane_b32 s78, v252, 19
	v_cndmask_b32_e32 v4, 0, v4, vcc
	v_bfe_u32 v6, v4, 16, 1
	v_add3_u32 v4, v4, v6, s33
	global_store_short_d16_hi v[2:3], v4, off offset:1536
	v_cndmask_b32_e64 v4, 0, 1, s[54:55]
	v_cndmask_b32_e64 v6, 0, 1, s[56:57]
	v_cndmask_b32_e64 v4, v6, v4, s[70:71]
	v_and_b32_e32 v4, 1, v4
	v_cmp_eq_u32_e32 vcc, 1, v4
	v_mul_f32_e32 v4, v0, v17
	s_add_i32 s89, s89, s78
	v_cndmask_b32_e32 v4, 0, v4, vcc
	v_bfe_u32 v6, v4, 16, 1
	v_add3_u32 v4, v4, v6, s33
	global_store_short_d16_hi v[2:3], v4, off offset:2048
	v_cndmask_b32_e64 v4, 0, 1, s[58:59]
	v_cndmask_b32_e64 v6, 0, 1, s[60:61]
	v_cndmask_b32_e64 v4, v6, v4, s[70:71]
	v_and_b32_e32 v4, 1, v4
	v_cmp_eq_u32_e32 vcc, 1, v4
	v_mul_f32_e32 v4, v0, v13
	v_readlane_b32 s77, v252, 18
	v_cndmask_b32_e32 v4, 0, v4, vcc
	v_bfe_u32 v6, v4, 16, 1
	v_add3_u32 v4, v4, v6, s33
	global_store_short_d16_hi v[2:3], v4, off offset:2560
	v_cndmask_b32_e64 v4, 0, 1, s[62:63]
	v_cndmask_b32_e64 v6, 0, 1, s[64:65]
	v_cndmask_b32_e64 v4, v6, v4, s[70:71]
	v_and_b32_e32 v4, 1, v4
	v_cmp_eq_u32_e32 vcc, 1, v4
	v_mul_f32_e32 v4, v0, v9
	v_mul_f32_e32 v0, v0, v5
	v_cndmask_b32_e32 v4, 0, v4, vcc
	v_bfe_u32 v6, v4, 16, 1
	v_add3_u32 v4, v4, v6, s33
	global_store_short_d16_hi v[2:3], v4, off offset:3072
	v_cndmask_b32_e64 v4, 0, 1, s[66:67]
	v_cndmask_b32_e64 v6, 0, 1, s[68:69]
	v_cndmask_b32_e64 v4, v6, v4, s[70:71]
	v_and_b32_e32 v4, 1, v4
	v_cmp_eq_u32_e32 vcc, 1, v4
	s_cmpk_gt_i32 s89, 0x1ff
	v_readlane_b32 s79, v252, 20
	v_cndmask_b32_e32 v0, 0, v0, vcc
	v_bfe_u32 v4, v0, 16, 1
	v_add3_u32 v0, v0, v4, s33
	global_store_short_d16_hi v[2:3], v0, off offset:3584
	s_cbranch_scc1 .LBB0_1163

.LBB0_1226:
	s_cmp_gt_u32 s13, 1
	s_cselect_b64 s[14:15], -1, 0
	s_and_b32 s12, s13, 1
	s_cmp_lt_u32 s13, 2
	s_mul_i32 s22, s12, 0x2100
	s_cbranch_scc1 .Lscan_nl
	s_waitcnt vmcnt(17)
	ds_write_b128 v194, v[44:47]
	ds_write_b128 v195, v[52:55]
	ds_write_b128 v196, v[56:59]
	ds_write_b128 v197, v[60:63]
	ds_write_b128 v198, v[48:51]
	ds_write_b128 v199, v[64:67]
	ds_write_b128 v201, v[84:87]
	ds_write_b128 v220, v[88:91]
	s_and_saveexec_b64 s[10:11], s[2:3]
	ds_write_b128 v137, v[40:43]
	s_or_b64 exec, exec, s[10:11]
	v_and_b32_sdwa v3, v92, v204 dst_sel:DWORD dst_unused:UNUSED_PAD src0_sel:WORD_1 src1_sel:DWORD
	v_add3_u32 v100, v92, v3, s33
	v_and_b32_sdwa v3, v95, v204 dst_sel:DWORD dst_unused:UNUSED_PAD src0_sel:WORD_1 src1_sel:DWORD
	v_and_b32_sdwa v101, v93, v204 dst_sel:DWORD dst_unused:UNUSED_PAD src0_sel:WORD_1 src1_sel:DWORD
	v_and_b32_sdwa v2, v94, v204 dst_sel:DWORD dst_unused:UNUSED_PAD src0_sel:WORD_1 src1_sel:DWORD
	v_add3_u32 v3, v95, v3, s33
	v_add3_u32 v101, v93, v101, s33
	v_add3_u32 v2, v94, v2, s33
	v_and_b32_e32 v3, 0xffff0000, v3
	v_and_b32_e32 v101, 0xffff0000, v101
	v_or_b32_sdwa v3, v3, v2 dst_sel:DWORD dst_unused:UNUSED_PAD src0_sel:DWORD src1_sel:WORD_1
	v_or_b32_sdwa v2, v101, v100 dst_sel:DWORD dst_unused:UNUSED_PAD src0_sel:DWORD src1_sel:WORD_1
	v_and_b32_sdwa v101, v96, v204 dst_sel:DWORD dst_unused:UNUSED_PAD src0_sel:WORD_1 src1_sel:DWORD
	v_add3_u32 v102, v96, v101, s33
	v_and_b32_sdwa v101, v99, v204 dst_sel:DWORD dst_unused:UNUSED_PAD src0_sel:WORD_1 src1_sel:DWORD
	v_and_b32_sdwa v103, v97, v204 dst_sel:DWORD dst_unused:UNUSED_PAD src0_sel:WORD_1 src1_sel:DWORD
	v_and_b32_sdwa v100, v98, v204 dst_sel:DWORD dst_unused:UNUSED_PAD src0_sel:WORD_1 src1_sel:DWORD
	v_add3_u32 v101, v99, v101, s33
	v_add3_u32 v103, v97, v103, s33
	v_add3_u32 v100, v98, v100, s33
	v_and_b32_e32 v101, 0xffff0000, v101
	v_and_b32_e32 v103, 0xffff0000, v103
	v_add_u32_e32 v0, s22, v179
	v_or_b32_sdwa v101, v101, v100 dst_sel:DWORD dst_unused:UNUSED_PAD src0_sel:DWORD src1_sel:WORD_1
	v_or_b32_sdwa v100, v103, v102 dst_sel:DWORD dst_unused:UNUSED_PAD src0_sel:DWORD src1_sel:WORD_1
	ds_write2_b64 v0, v[2:3], v[100:101] offset1:4

.LBB0_1236:
	s_andn2_b64 vcc, exec, s[10:11]
	s_lshl_b32 s10, s12, 7
	s_mov_b32 s100, 0
	s_cbranch_vccnz .LBB0_1240
	s_lshl_b32 s99, s12, 15
	s_mov_b32 s100, 1
	s_lshl_b32 s16, s10, 11
	s_mov_b32 s17, 0
	v_lshl_add_u64 v[2:3], v[148:149], 0, s[16:17]
	s_movk_i32 s16, 0x1000
	global_load_dwordx4 v[44:47], v[2:3], off
	v_lshl_add_u64 v[2:3], v[2:3], 0, s[16:17]
	global_load_dwordx4 v[52:55], v[2:3], off
	v_lshl_add_u64 v[2:3], v[2:3], 0, s[16:17]
	global_load_dwordx4 v[56:59], v[2:3], off
	v_lshl_add_u64 v[2:3], v[2:3], 0, s[16:17]
	global_load_dwordx4 v[60:63], v[2:3], off
	v_lshl_add_u64 v[2:3], v[2:3], 0, s[16:17]
	global_load_dwordx4 v[48:51], v[2:3], off
	v_lshl_add_u64 v[2:3], v[2:3], 0, s[16:17]
	global_load_dwordx4 v[64:67], v[2:3], off
	v_lshl_add_u64 v[2:3], v[2:3], 0, s[16:17]
	global_load_dwordx4 v[84:87], v[2:3], off
	v_lshl_add_u64 v[2:3], v[2:3], 0, s[16:17]
	global_load_dwordx4 v[88:91], v[2:3], off
	s_and_saveexec_b64 s[12:13], s[2:3]
	s_cbranch_execz .Lscan_ldq_gA
	s_lshl_b32 s16, s10, 12
	v_lshl_add_u64 v[2:3], v[152:153], 0, s[16:17]
	global_load_dwordx4 v[40:43], v[2:3], off

.LBB0_1242:
	s_or_b64 exec, exec, s[16:17]
	v_lshl_add_u32 v0, s23, 1, v158
	v_lshl_add_u32 v2, v159, 1, v0
	s_waitcnt lgkmcnt(0)
	s_barrier
	v_lshl_add_u32 v3, v160, 1, v0
	ds_read_b128 v[112:115], v2
	ds_read_b128 v[108:111], v3
	v_lshl_add_u32 v2, v161, 1, v0
	v_lshl_add_u32 v0, v162, 1, v0
	ds_read_b128 v[104:107], v2
	ds_read_b128 v[100:103], v0
	s_andn2_b64 vcc, exec, s[14:15]
	s_cbranch_vccnz .LBB0_1248
	s_setprio 1
	v_add_u32_e32 v0, s22, v181
	v_add_u32_e32 v2, v180, v163
	v_add_u32_e32 v3, v180, v165
	ds_read_b128 v[238:241], v2
	ds_read_b128 v[242:245], v0
	ds_read_b128 v[246:249], v3
	ds_read_b128 v[116:119], v0 offset:64
	v_add_u32_e32 v2, v180, v169
	v_add_u32_e32 v3, v180, v173
	s_waitcnt lgkmcnt(2)
	v_mfma_f32_16x16x32_bf16 v[234:237], v[238:241], v[242:245], 0
	ds_read_b128 v[238:241], v2
	ds_read_b128 v[242:245], v0 offset:128
	s_waitcnt lgkmcnt(2)
	v_mfma_f32_16x16x32_bf16 v[230:233], v[246:249], v[116:119], 0
	ds_read_b128 v[246:249], v3
	ds_read_b128 v[116:119], v0 offset:192
	s_waitcnt lgkmcnt(2)
	v_mfma_f32_16x16x32_bf16 v[234:237], v[238:241], v[242:245], v[234:237]
	ds_read_b128 v[238:241], v221
	ds_read_b128 v[242:245], v0 offset:256
	s_waitcnt lgkmcnt(2)
	v_mfma_f32_16x16x32_bf16 v[230:233], v[246:249], v[116:119], v[230:233]
	ds_read_b128 v[246:249], v222
	ds_read_b128 v[116:119], v0 offset:320
	s_waitcnt lgkmcnt(2)
	v_mfma_f32_16x16x32_bf16 v[234:237], v[238:241], v[242:245], v[234:237]
	ds_read_b128 v[238:241], v223
	ds_read_b128 v[242:245], v0 offset:384
	s_waitcnt lgkmcnt(2)
	v_mfma_f32_16x16x32_bf16 v[230:233], v[246:249], v[116:119], v[230:233]
	ds_read_b128 v[246:249], v224
	ds_read_b128 v[116:119], v0 offset:448
	s_waitcnt lgkmcnt(2)
	v_mfma_f32_16x16x32_bf16 v[234:237], v[238:241], v[242:245], v[234:237]
	s_waitcnt lgkmcnt(0)
	v_mfma_f32_16x16x32_bf16 v[230:233], v[246:249], v[116:119], v[230:233]
	s_waitcnt vmcnt(22)
	v_mfma_f32_16x16x32_bf16 v[116:119], v[80:83], v[112:115], 0
	v_mfma_f32_16x16x32_bf16 v[116:119], v[76:79], v[108:111], v[116:119]
	v_mfma_f32_16x16x32_bf16 v[116:119], v[72:75], v[104:107], v[116:119]
	v_mfma_f32_16x16x32_bf16 v[116:119], v[68:71], v[100:103], v[116:119]
	s_setprio 0
	s_cmp_eq_u32 s100, 0
	s_cbranch_scc1 .Lscan_ldq_donea
	s_mov_b32 s16, s99
	s_mov_b32 s17, 0
	v_lshl_add_u64 v[2:3], v[150:151], 0, s[16:17]
	global_load_dwordx4 v[80:83], v[2:3], off
	global_load_dwordx4 v[76:79], v[2:3], off offset:1024
	global_load_dwordx4 v[72:75], v[2:3], off offset:2048
	global_load_dwordx4 v[68:71], v[2:3], off offset:3072
.Lscan_ldq_donea:
	v_add_f32_e32 v0, v234, v230
	s_nop 5
	v_fma_f32 v3, v226, v0, v116
	v_add_f32_e32 v0, v235, v231
	v_fma_f32 v2, v227, v0, v117
	v_add_f32_e32 v0, v236, v232
	v_add_f32_e32 v116, v237, v233
	v_fma_f32 v0, v228, v0, v118
	v_fmac_f32_e32 v119, v229, v116
	v_mul_f32_e32 v116, v3, v3
	v_mul_f32_e32 v118, v2, v2
	v_mul_f32_e32 v141, v0, v0
	v_mul_f32_e32 v230, v119, v119
	v_mov_b32_dpp v116, v116 quad_perm:[1,0,3,2] row_mask:0xf bank_mask:0xf bound_ctrl:1
	v_mov_b32_dpp v118, v118 quad_perm:[1,0,3,2] row_mask:0xf bank_mask:0xf bound_ctrl:1
	v_mov_b32_dpp v141, v141 quad_perm:[1,0,3,2] row_mask:0xf bank_mask:0xf bound_ctrl:1
	v_mov_b32_dpp v230, v230 quad_perm:[1,0,3,2] row_mask:0xf bank_mask:0xf bound_ctrl:1
	v_fmac_f32_e32 v116, v3, v3
	v_fmac_f32_e32 v118, v2, v2
	v_fmac_f32_e32 v141, v0, v0
	v_fmac_f32_e32 v230, v119, v119
	v_add_f32_dpp v116, v116, v116 quad_perm:[2,3,0,1] row_mask:0xf bank_mask:0xf bound_ctrl:1
	v_add_f32_dpp v118, v118, v118 quad_perm:[2,3,0,1] row_mask:0xf bank_mask:0xf bound_ctrl:1
	v_add_f32_dpp v141, v141, v141 quad_perm:[2,3,0,1] row_mask:0xf bank_mask:0xf bound_ctrl:1
	v_add_f32_dpp v230, v230, v230 quad_perm:[2,3,0,1] row_mask:0xf bank_mask:0xf bound_ctrl:1
	v_add_f32_dpp v116, v116, v116 row_half_mirror row_mask:0xf bank_mask:0xf bound_ctrl:1
	v_add_f32_dpp v118, v118, v118 row_half_mirror row_mask:0xf bank_mask:0xf bound_ctrl:1
	v_add_f32_dpp v141, v141, v141 row_half_mirror row_mask:0xf bank_mask:0xf bound_ctrl:1
	v_add_f32_dpp v230, v230, v230 row_half_mirror row_mask:0xf bank_mask:0xf bound_ctrl:1
	v_mov_b32_dpp v117, v116 row_mirror row_mask:0xf bank_mask:0xf bound_ctrl:1
	v_mov_b32_dpp v139, v118 row_mirror row_mask:0xf bank_mask:0xf bound_ctrl:1
	v_mov_b32_dpp v147, v141 row_mirror row_mask:0xf bank_mask:0xf bound_ctrl:1
	v_mov_b32_dpp v231, v230 row_mirror row_mask:0xf bank_mask:0xf bound_ctrl:1
	s_and_saveexec_b64 s[14:15], s[4:5]
	s_cbranch_execz .LBB0_1245
	s_ashr_i32 s9, s8, 31
	s_lshl_b64 s[16:17], s[8:9], 9
	v_lshl_add_u64 v[232:233], v[154:155], 0, s[16:17]
	v_add_f32_e32 v116, v116, v117
	v_add_f32_e32 v230, v230, v231
	v_add_f32_e32 v141, v141, v147
	v_add_f32_e32 v118, v118, v139
	global_store_dword v[232:233], v116, off
	global_store_dword v[232:233], v118, off offset:512
	global_store_dword v[232:233], v141, off offset:1024
	global_store_dword v[232:233], v230, off offset:1536

.LBB0_1248:
	s_cmp_eq_u32 s100, 0
	s_cbranch_scc1 .Lscan_ldq_doneb
	s_mov_b32 s16, s99
	s_mov_b32 s17, 0
	v_lshl_add_u64 v[2:3], v[150:151], 0, s[16:17]
	global_load_dwordx4 v[80:83], v[2:3], off
	global_load_dwordx4 v[76:79], v[2:3], off offset:1024
	global_load_dwordx4 v[72:75], v[2:3], off offset:2048
	global_load_dwordx4 v[68:71], v[2:3], off offset:3072
